# phase0: blocks that run a modulation item hand their fifth tile-conversion item to blocks that had four
# speedup vs baseline: 1.0756x; 1.0054x over previous
.LBB0_353:
	v_readlane_b32 s0, v248, 3
	v_readlane_b32 s1, v248, 4
	s_load_dword s0, s[0:1], 0x0
	v_readlane_b32 s1, v248, 0
	s_waitcnt lgkmcnt(0)
	s_add_i32 s48, s48, s0
	s_add_i32 s0, s1, 0x800
	s_cmp_lg_u32 s48, s0
	s_cbranch_scc1 .Lp0_keep
	s_cmp_lt_u32 s1, 0xc0
	s_cbranch_scc1 .LBB0_401
	s_cmp_lt_u32 s1, 0x121
	s_cbranch_scc1 .Lp0_keep
	s_cmp_gt_u32 s1, 0x1e0
	s_cbranch_scc1 .Lp0_keep
	s_addk_i32 s48, 0xfedf
.Lp0_keep:
	s_cmpk_gt_i32 s48, 0x920
	s_cbranch_scc1 .LBB0_401
